# v23 plus attention v_max fold plus SSD output phase k-step-1 state fragments requested with k-step 0 (no dummy loads)
# speedup vs baseline: 1.0040x; 1.0040x over previous
; __device__ __forceinline__ unsigned pk2(float lo, float hi) { const cvt_f2 v = {lo, hi}; const cvt_b2 r = __builtin_convertvector(v, cvt_b2); return __builtin_bit_cast(unsigned, r); }
; __device__ __forceinline__ void ssd_out_phase(Frame& F, bf16* Ydst) {
;     ...
;         for (int ks = 0; ks < 4; ++ks) {
;             bf16x8 af[4], bfr[4];
; #pragma unroll
;             for (int pt = 0; pt < 4; ++pt) { const int pp = 32 * (pt >> 1) + 8 * (l15 >> 2) + 4 * (pt & 1) + (l15 & 3), n0 = 32 * ks + 8 * g4;
;                 if (!smp) af[pt] = *(const bf16x8*)(ST + ((size_t)c * 64 + h) * 8192 + (((pp >> 4) * 4 + ks) * 64 + g4 * 16 + (pp & 15)) * 8);
;                 else { const float* sp = F.state_ssm + (((size_t)(c - 256) * 64 + h) * 64 + pp) * 128 + n0; const f32x4 a = *(const f32x4*)sp, b = *(const f32x4*)(sp + 4);
;                     v4u w; w.x = pk2(a.x, a.y); w.y = pk2(a.z, a.w); w.z = pk2(b.x, b.y); w.w = pk2(b.z, b.w); af[pt] = __builtin_bit_cast(bf16x8, w); } }
.LBB0_1370:
	s_or_b64 exec, exec, s[34:35]
	s_ashr_i32 s1, s0, 31
	s_lshl_b64 s[16:17], s[0:1], 20
	s_add_u32 s1, s42, s16
	s_addc_u32 s34, s43, s17
	s_lshl_b64 s[16:17], s[26:27], 14
	s_add_u32 s16, s1, s16
	v_lshrrev_b32_e32 v210, 2, v205
	s_addc_u32 s17, s34, s17
	s_addk_i32 s0, 0xff00
	s_mov_b32 s1, s27
	v_lshlrev_b32_e32 v42, 3, v210
	v_and_b32_e32 v43, 3, v209
	s_lshl_b64 s[0:1], s[0:1], 12
	s_lshl_b64 s[34:35], s[26:27], 6
	s_add_u32 s54, s34, s0
	v_or_b32_e32 v154, v42, v43
	v_cndmask_b32_e64 v2, 0, 1, s[2:3]
	v_and_b32_e32 v206, 48, v209
	s_addc_u32 s53, s35, s1
	v_cmp_ne_u32_e64 s[0:1], 1, v2
	s_andn2_b64 vcc, exec, s[2:3]
	v_lshl_or_b32 v2, v210, 7, v154
	s_movk_i32 s2, 0x10b
	s_mov_b64 s[34:35], -1
	v_and_or_b32 v122, v2, s2, v206
	s_cbranch_vccnz .LBB0_1372
	v_lshlrev_b32_e32 v2, 4, v122
	global_load_dwordx4 v[34:37], v2, s[16:17]
	global_load_dwordx4 v[134:137], v2, s[16:17] offset:1024
	s_mov_b64 s[34:35], 0

; __device__ __forceinline__ unsigned pk2(float lo, float hi) { const cvt_f2 v = {lo, hi}; const cvt_b2 r = __builtin_convertvector(v, cvt_b2); return __builtin_bit_cast(unsigned, r); }
; __device__ __forceinline__ void ssd_out_phase(Frame& F, bf16* Ydst) {
;     ...
;             for (int pt = 0; pt < 4; ++pt) { const int pp = 32 * (pt >> 1) + 8 * (l15 >> 2) + 4 * (pt & 1) + (l15 & 3), n0 = 32 * ks + 8 * g4;
;                 if (!smp) af[pt] = *(const bf16x8*)(ST + ((size_t)c * 64 + h) * 8192 + (((pp >> 4) * 4 + ks) * 64 + g4 * 16 + (pp & 15)) * 8);
;                 else { const float* sp = F.state_ssm + (((size_t)(c - 256) * 64 + h) * 64 + pp) * 128 + n0; const f32x4 a = *(const f32x4*)sp, b = *(const f32x4*)(sp + 4);
;                     v4u w; w.x = pk2(a.x, a.y); w.y = pk2(a.z, a.w); w.z = pk2(b.x, b.y); w.w = pk2(b.z, b.w); af[pt] = __builtin_bit_cast(bf16x8, w); } }
.LBB0_1374:
	v_or_b32_e32 v44, 4, v43
	v_or_b32_e32 v158, v42, v44
	v_lshl_or_b32 v4, v210, 7, v158
	s_movk_i32 s34, 0x10f
	s_mov_b64 s[2:3], -1
	s_and_b64 vcc, exec, s[0:1]
	v_and_or_b32 v123, v4, s34, v206
	s_cbranch_vccnz .LBB0_1376
	v_lshlrev_b32_e32 v4, 4, v123
	global_load_dwordx4 v[50:53], v4, s[16:17]
	global_load_dwordx4 v[138:141], v4, s[16:17] offset:1024
	s_mov_b64 s[2:3], 0

; __device__ __forceinline__ unsigned pk2(float lo, float hi) { const cvt_f2 v = {lo, hi}; const cvt_b2 r = __builtin_convertvector(v, cvt_b2); return __builtin_bit_cast(unsigned, r); }
; __device__ __forceinline__ void ssd_out_phase(Frame& F, bf16* Ydst) {
;     ...
;             for (int pt = 0; pt < 4; ++pt) { const int pp = 32 * (pt >> 1) + 8 * (l15 >> 2) + 4 * (pt & 1) + (l15 & 3), n0 = 32 * ks + 8 * g4;
;                 if (!smp) af[pt] = *(const bf16x8*)(ST + ((size_t)c * 64 + h) * 8192 + (((pp >> 4) * 4 + ks) * 64 + g4 * 16 + (pp & 15)) * 8);
;                 else { const float* sp = F.state_ssm + (((size_t)(c - 256) * 64 + h) * 64 + pp) * 128 + n0; const f32x4 a = *(const f32x4*)sp, b = *(const f32x4*)(sp + 4);
;                     v4u w; w.x = pk2(a.x, a.y); w.y = pk2(a.z, a.w); w.z = pk2(b.x, b.y); w.w = pk2(b.z, b.w); af[pt] = __builtin_bit_cast(bf16x8, w); } }
.LBB0_1378:
	v_or_b32_e32 v42, 32, v42
	v_or_b32_e32 v43, v42, v43
	v_lshl_or_b32 v4, v42, 4, v43
	s_movk_i32 s34, 0x30b
	s_mov_b64 s[2:3], -1
	s_and_b64 vcc, exec, s[0:1]
	v_and_or_b32 v4, v4, s34, v206
	s_cbranch_vccnz .LBB0_1380
	v_lshlrev_b32_e32 v45, 4, v4
	global_load_dwordx4 v[106:109], v45, s[16:17]
	global_load_dwordx4 v[142:145], v45, s[16:17] offset:1024
	s_mov_b64 s[2:3], 0

; __device__ __forceinline__ unsigned pk2(float lo, float hi) { const cvt_f2 v = {lo, hi}; const cvt_b2 r = __builtin_convertvector(v, cvt_b2); return __builtin_bit_cast(unsigned, r); }
; __device__ __forceinline__ void ssd_out_phase(Frame& F, bf16* Ydst) {
;     ...
;             for (int pt = 0; pt < 4; ++pt) { const int pp = 32 * (pt >> 1) + 8 * (l15 >> 2) + 4 * (pt & 1) + (l15 & 3), n0 = 32 * ks + 8 * g4;
;                 if (!smp) af[pt] = *(const bf16x8*)(ST + ((size_t)c * 64 + h) * 8192 + (((pp >> 4) * 4 + ks) * 64 + g4 * 16 + (pp & 15)) * 8);
;                 else { const float* sp = F.state_ssm + (((size_t)(c - 256) * 64 + h) * 64 + pp) * 128 + n0; const f32x4 a = *(const f32x4*)sp, b = *(const f32x4*)(sp + 4);
;                     v4u w; w.x = pk2(a.x, a.y); w.y = pk2(a.z, a.w); w.z = pk2(b.x, b.y); w.w = pk2(b.z, b.w); af[pt] = __builtin_bit_cast(bf16x8, w); } }
.LBB0_1382:
	v_or_b32_e32 v43, v42, v44
	v_lshl_or_b32 v42, v42, 4, v43
	s_movk_i32 s34, 0x30f
	s_mov_b64 s[2:3], -1
	s_and_b64 vcc, exec, s[0:1]
	v_and_or_b32 v185, v42, s34, v206
	s_cbranch_vccnz .LBB0_1384
	v_lshlrev_b32_e32 v42, 4, v185
	global_load_dwordx4 v[118:121], v42, s[16:17]
	global_load_dwordx4 v[146:149], v42, s[16:17] offset:1024
	s_mov_b64 s[2:3], 0
